# v55 plus: scan-chain intra-chunk QK fragment reads issued up front
# baseline (speedup 1.0000x reference)
; #define MFMA16(a, b, c) __builtin_amdgcn_mfma_f32_16x16x32_bf16((a), (b), (c), 0, 0, 0)
; DI void dn_scan_chain(CParams& p, int it, int S, char* lds) {
;     ...
;     {
;       f32x4 QK[4];
; #pragma unroll
;       for (int t = 0; t < 4; ++t) QK[t] = f32x4{0.f, 0.f, 0.f, 0.f};
; #pragma unroll
;       for (int ks = 0; ks < 2; ++ks) {
;         const bf16x8 bfk = *(const bf16x8*)(Kimg + (16 * w + l15) * 72 + 32 * ks + 8 * g4);
; #pragma unroll
;         for (int rt = 0; rt < 4; ++rt) {
;           const bf16x8 afq = *(const bf16x8*)(Qimg + (16 * rt + l15) * 72 + 32 * ks + 8 * g4);
;           QK[rt] = MFMA16(afq, bfk, QK[rt]);
;         }
;       }
;       const float gcj = gcs[e_col];
; #pragma unroll
;       for (int rt = 0; rt < 4; ++rt)
; #pragma unroll
;         for (int r = 0; r < 4; ++r) {
;           const int i = 16 * rt + 4 * g4 + r;
;           const float ee = __expf(fminf(gcs[i] - gcj, 0.f));
;           Iimg[i * 72 + e_col] = f2bf((i >= e_col) ? QK[rt][r] * ee : 0.f);
;         }
;     }
.LBB0_616:
	v_and_b32_e32 v68, 15, v52
	v_bfe_u32 v69, v52, 4, 2
	v_lshlrev_b32_e32 v54, 4, v69
	v_mul_u32_u24_e32 v70, 0x90, v68
	v_ashrrev_i32_e32 v0, 2, v52
	v_add3_u32 v67, 16, v54, v70
	v_bfi_b32 v98, -16, v0, v52
	s_waitcnt lgkmcnt(0)
	s_barrier
	v_lshl_add_u32 v96, v69, 4, 16
	ds_read_b128 v[80:83], v96 offset:55296
	ds_read_b128 v[84:87], v96 offset:55360
	ds_read_b128 v[88:91], v96 offset:55424
	ds_read_b128 v[92:95], v96 offset:55488
	v_mul_lo_u32 v0, v98, s12
	v_add_u32_e32 v0, 16, v0
	v_add_u32_e32 v66, v0, v54
	s_movk_i32 s6, 0xff74
	ds_read_b128 v[162:165], v66 offset:27648
	ds_read_b128 v[130:133], v67 offset:18432
	ds_read_b128 v[138:141], v67 offset:20736
	ds_read_b128 v[146:149], v67 offset:23040
	ds_read_b128 v[154:157], v67 offset:25344
	ds_read_b128 v[166:169], v66 offset:27712
	ds_read_b128 v[134:137], v67 offset:18496
	ds_read_b128 v[142:145], v67 offset:20800
	ds_read_b128 v[150:153], v67 offset:23104
	ds_read_b128 v[158:161], v67 offset:25408
	s_waitcnt lgkmcnt(8)
	v_mfma_f32_16x16x32_bf16 v[62:65], v[130:133], v[162:165], 0
	s_waitcnt lgkmcnt(7)
	v_mfma_f32_16x16x32_bf16 v[58:61], v[138:141], v[162:165], 0
	s_waitcnt lgkmcnt(6)
	v_mfma_f32_16x16x32_bf16 v[54:57], v[146:149], v[162:165], 0
	s_waitcnt lgkmcnt(5)
	v_mfma_f32_16x16x32_bf16 v[50:53], v[154:157], v[162:165], 0
	s_waitcnt lgkmcnt(3)
	v_mfma_f32_16x16x32_bf16 v[62:65], v[134:137], v[166:169], v[62:65]
	s_waitcnt lgkmcnt(2)
	v_mfma_f32_16x16x32_bf16 v[58:61], v[142:145], v[166:169], v[58:61]
	s_waitcnt lgkmcnt(1)
	v_mfma_f32_16x16x32_bf16 v[54:57], v[150:153], v[166:169], v[54:57]
	s_waitcnt lgkmcnt(0)
	v_mfma_f32_16x16x32_bf16 v[50:53], v[158:161], v[166:169], v[50:53]
	v_mad_u64_u32 v[66:67], s[6:7], v98, s6, v[0:1]
	ds_read_b32 v67, v66 offset:55296
	v_lshlrev_b32_e32 v0, 2, v69
	v_cmp_ge_i32_e64 s[44:45], v0, v98
	v_mov_b32_e32 v72, 0
	v_lshl_add_u32 v71, v0, 2, 16
	v_mov_b32_e32 v73, 0
	v_lshlrev_b32_e32 v126, 3, v69
	v_add3_u32 v126, 16, v126, v70
	v_mul_u32_u24_e32 v127, 0x240, v69
	v_lshl_add_u32 v128, v98, 1, 16
	v_add_u32_e32 v127, v127, v128
	ds_read_b64 v[130:131], v126 offset:9216
	ds_read_b64 v[132:133], v126 offset:9248
	ds_read_b64 v[138:139], v126 offset:18432
	ds_read_b64 v[140:141], v126 offset:18464
	ds_read_b64 v[134:135], v126 offset:9280
	ds_read_b64 v[136:137], v126 offset:9312
	ds_read_b64 v[142:143], v126 offset:18496
	ds_read_b64 v[144:145], v126 offset:18528
	ds_read_b64 v[146:147], v126 offset:11520
	ds_read_b64 v[148:149], v126 offset:11552
	ds_read_b64 v[154:155], v126 offset:20736
	ds_read_b64 v[156:157], v126 offset:20768
	ds_read_b64 v[150:151], v126 offset:11584
	ds_read_b64 v[152:153], v126 offset:11616
	ds_read_b64 v[158:159], v126 offset:20800
	ds_read_b64 v[160:161], v126 offset:20832
	ds_read_b64 v[162:163], v126 offset:13824
	ds_read_b64 v[164:165], v126 offset:13856
	ds_read_b64 v[170:171], v126 offset:23040
	ds_read_b64 v[172:173], v126 offset:23072
	ds_read_b64 v[166:167], v126 offset:13888
	ds_read_b64 v[168:169], v126 offset:13920
	ds_read_b64 v[174:175], v126 offset:23104
	ds_read_b64 v[176:177], v126 offset:23136
	ds_read_b64 v[178:179], v126 offset:16128
	ds_read_b64 v[180:181], v126 offset:16160
	ds_read_b64 v[186:187], v126 offset:25344
	ds_read_b64 v[188:189], v126 offset:25376
	ds_read_b64 v[182:183], v126 offset:16192
	ds_read_b64 v[184:185], v126 offset:16224
	ds_read_b64 v[190:191], v126 offset:25408
	ds_read_b64 v[192:193], v126 offset:25440
	ds_read_u16 v194, v127 offset:0
	ds_read_u16 v195, v127 offset:144
	ds_read_u16 v196, v127 offset:288
	ds_read_u16 v197, v127 offset:432
	ds_read_u16 v198, v127 offset:2304
	ds_read_u16 v199, v127 offset:2448
	ds_read_u16 v200, v127 offset:2592
	ds_read_u16 v201, v127 offset:2736
	ds_read_u16 v202, v127 offset:4608
	ds_read_u16 v203, v127 offset:4752
	ds_read_u16 v204, v127 offset:4896
	ds_read_u16 v205, v127 offset:5040
	ds_read_u16 v206, v127 offset:6912
	ds_read_u16 v207, v127 offset:7056
	ds_read_u16 v208, v127 offset:7200
	ds_read_u16 v209, v127 offset:7344
	s_waitcnt lgkmcnt(0)
	s_and_saveexec_b64 s[6:7], s[44:45]
	s_cbranch_execz .LBB0_618
	v_sub_f32_e32 v73, v80, v67
	v_min_f32_e32 v73, 0, v73
	v_mul_f32_e32 v73, 0x3fb8aa3b, v73
	v_exp_f32_e32 v73, v73
	s_nop 0
	v_mul_f32_e32 v62, v62, v73
	v_cvt_pk_bf16_f32 v73, v62, s0
